# baseline (speedup 1.0000x reference)
; #define SWRITE_KR(b) do { int kc = sc * 2; *(bf16x8*)(K_lds + (b) * SHM_K + KSWZ(sr, kc)) = ks0; *(bf16x8*)(K_lds + (b) * SHM_K + KSWZ(32 + sr, kc)) = ks1; \
;     *(bf16x8*)(R_lds + (b) * SHM_R + RSWZ(rr_, rc_ * 2)) = rs0; } while (0)
; #define SWRITE_V(b) do { *(bf16x8*)(V_lds + (b) * SHM_V + RSWZ(vd, vc * 16)) = vs0; *(bf16x8*)(V_lds + (b) * SHM_V + RSWZ(vd + 64, vc * 16)) = vs1; } while (0)
; #define SWAIT() asm volatile("s_waitcnt vmcnt(0)" ::: "memory")
; #define RESC(a) do { if (__any((a) < 1.f)) { if (hi == 0) al_l[r32] = (a); asm volatile("s_waitcnt lgkmcnt(0)" ::: "memory"); \
;     _Pragma("unroll") for (int d = 0; d < 4; ++d) _Pragma("unroll") for (int r = 0; r < 16; ++r) o[d][r] *= al_l[crow(r, hi)]; } } while (0)
; DEVI void partialSM(f32x16& p0, f32x16& p1, float& m_reg, float& mn, float& alpha) {
;     ...
;   float mnC = -mn * C;
; #pragma unroll
;   for (int r = 0; r < 16; ++r) p0[r] = fmaf(p0[r], C, mnC);
; #pragma unroll
;   for (int r = 0; r < 16; ++r) p1[r] = fmaf(p1[r], C, mnC);
; #pragma unroll
;   for (int r = 0; r < 16; ++r) p0[r] = __builtin_amdgcn_exp2f(p0[r]);
; DEVI void attn_item(const u16* __restrict__ Qb, const u16* __restrict__ KNh, const u16* __restrict__ VTh, int Lpad, const u16* __restrict__ KRb,
;                     const u16* __restrict__ SZb, u16* __restrict__ AOb, int NT, char* lds, const int wid_s_) {
;     ...
;     SWRITE_KR(1);
;     __syncthreads(); SWAIT(); SWRITE_V(1);
;     RESC(alA); __syncthreads();
;   }
.LBB0_989:
	v_cndmask_b32_e64 v222, v89, v222, s[8:9]
	v_mul_f32_e32 v90, 0xbdd53b94, v222
	v_mov_b32_e32 v129, v90
	v_fmamk_f32 v64, v64, 0x3dd53b94, v90
	v_fmamk_f32 v65, v65, 0x3dd53b94, v90
	v_fmamk_f32 v66, v66, 0x3dd53b94, v90
	v_fmamk_f32 v67, v67, 0x3dd53b94, v90
	v_fmamk_f32 v68, v68, 0x3dd53b94, v90
	v_fmamk_f32 v69, v69, 0x3dd53b94, v90
	v_fmamk_f32 v70, v70, 0x3dd53b94, v90
	v_fmamk_f32 v71, v71, 0x3dd53b94, v90
	v_fmamk_f32 v89, v229, 0x3dd53b94, v90
	v_fmamk_f32 v91, v228, 0x3dd53b94, v90
	v_fmamk_f32 v92, v226, 0x3dd53b94, v90
	v_fmamk_f32 v93, v225, 0x3dd53b94, v90
	v_fmamk_f32 v94, v227, 0x3dd53b94, v90
	v_fmamk_f32 v95, v223, 0x3dd53b94, v90
	v_fmamk_f32 v128, v173, 0x3dd53b94, v90
	v_fmac_f32_e32 v129, 0x3dd53b94, v172
	v_exp_f32_e32 v231, v64
	v_exp_f32_e32 v235, v65
	v_exp_f32_e32 v230, v66
	v_exp_f32_e32 v232, v67
	v_exp_f32_e32 v233, v68
	v_exp_f32_e32 v236, v69
	v_exp_f32_e32 v234, v70
	v_exp_f32_e32 v237, v71
	v_exp_f32_e32 v156, v89
	v_exp_f32_e32 v157, v91
	v_exp_f32_e32 v158, v92
	v_exp_f32_e32 v159, v93
	v_exp_f32_e32 v228, v94
	v_exp_f32_e32 v229, v95
	v_exp_f32_e32 v154, v128
	v_exp_f32_e32 v155, v129
	v_add_f32_e32 v64, v204, v221
	v_fmac_f32_e32 v64, v220, v182
	v_add_f32_e32 v182, v170, v171
	v_add_u32_e32 v166, 0x4000, v166
	s_add_i32 s1, s2, 2
	v_pk_fma_f32 v[80:81], v[80:81], s[80:81], v[90:91] op_sel_hi:[1,0,0]
	v_pk_fma_f32 v[152:153], v[82:83], s[80:81], v[90:91] op_sel_hi:[1,0,0]
	v_pk_fma_f32 v[150:151], v[84:85], s[80:81], v[90:91] op_sel_hi:[1,0,0]
	v_pk_fma_f32 v[148:149], v[86:87], s[80:81], v[90:91] op_sel_hi:[1,0,0]
	v_pk_fma_f32 v[142:143], v[78:79], s[80:81], v[90:91] op_sel_hi:[1,0,0]
	v_pk_fma_f32 v[146:147], v[76:77], s[80:81], v[90:91] op_sel_hi:[1,0,0]
	v_pk_fma_f32 v[140:141], v[74:75], s[80:81], v[90:91] op_sel_hi:[1,0,0]
	v_pk_fma_f32 v[144:145], v[72:73], s[80:81], v[90:91] op_sel_hi:[1,0,0]
	v_fmac_f32_e32 v182, v64, v224
	v_add_u32_e32 v162, s82, v162
	v_add_u32_e32 v164, s82, v164
	s_cmp_ge_u32 s2, s4
	v_add_u32_e32 v168, 0x80000, v168
	s_cbranch_scc1 .Lhl_skip
	global_load_dwordx4 v[128:131], v168, s[36:37] offset:3072
	v_add_u32_e32 v163, 0x20000, v168
	global_load_dwordx4 v[132:135], v163, s[36:37] offset:3072
	global_load_dwordx4 v[136:139], v166, s[36:37] offset:3072
	s_mov_b32 s2, s1
	v_mov_b32_e32 v220, v88
.Lhl_skip:
	s_waitcnt lgkmcnt(0)
	s_barrier
	s_cbranch_scc0 .LBB0_981
